# norm2 phase: hand-written row loop, all loads of a row issued together and the next row prefetched (the baseline waited after nearly every load)
# speedup vs baseline: 1.0128x; 1.0091x over previous
.LBB0_1071:
	s_or_b64 exec, exec, s[2:3]
	v_mov_b32_e32 v1, v222
	s_barrier
	v_readlane_b32 s2, v254, 57
	v_ashrrev_i32_e32 v2, 6, v1
	s_nop 0
	v_add_u32_e32 v18, s2, v2
	v_cmp_gt_i32_e32 vcc, s6, v18
	s_and_saveexec_b64 s[2:3], vcc
	s_cbranch_execz .LBB0_1078
	v_readfirstlane_b32 s7, v18
	v_mbcnt_lo_u32_b32 v10, -1, 0
	v_mbcnt_hi_u32_b32 v10, -1, v10
	v_lshlrev_b32_e32 v2, 4, v10
	v_lshlrev_b32_e32 v3, 3, v10
	v_xor_b32_e32 v4, 32, v10
	v_lshlrev_b32_e32 v4, 2, v4
	v_xor_b32_e32 v5, 16, v10
	v_lshlrev_b32_e32 v5, 2, v5
	v_xor_b32_e32 v6, 8, v10
	v_lshlrev_b32_e32 v6, 2, v6
	v_xor_b32_e32 v7, 4, v10
	v_lshlrev_b32_e32 v7, 2, v7
	v_xor_b32_e32 v8, 2, v10
	v_lshlrev_b32_e32 v8, 2, v8
	v_xor_b32_e32 v9, 1, v10
	v_lshlrev_b32_e32 v9, 2, v9
	v_readlane_b32 s22, v254, 12
	v_readlane_b32 s23, v254, 13
	v_readlane_b32 s24, v254, 55
	v_readlane_b32 s25, v254, 56
	v_readlane_b32 s20, v254, 14
	v_readlane_b32 s21, v254, 15
	v_readlane_b32 s18, v254, 60
	v_readlane_b32 s19, v254, 61
	v_readlane_b32 s5, v255, 47
	s_lshl_b32 s5, s5, 12
	s_add_u32 s18, s18, s5
	s_addc_u32 s19, s19, 0
	s_nop 1
	global_load_dwordx4 v[20:23], v2, s[18:19] offset:0
	global_load_dwordx4 v[24:27], v2, s[18:19] offset:1024
	global_load_dwordx4 v[28:31], v2, s[18:19] offset:2048
	global_load_dwordx4 v[32:35], v2, s[18:19] offset:3072
	s_cmp_lt_u32 s7, 0x8000
	s_cselect_b32 s10, s22, s24
	s_cselect_b32 s11, s23, s25
	s_cselect_b32 s5, s7, 0x8000
	s_and_b32 s26, s7, 0x7fff
	s_lshl_b32 s27, s26, 12
	s_lshr_b32 s26, s26, 20
	s_add_u32 s10, s10, s27
	s_addc_u32 s11, s11, s26
	s_lshr_b32 s5, s5, 11
	s_add_i32 s5, s5, s54
	s_mul_i32 s5, s5, 0x6000
	s_add_u32 s14, s20, s5
	s_addc_u32 s15, s21, 0
	s_add_u32 s16, s14, 0x3000
	s_addc_u32 s17, s15, 0
	s_add_u32 s14, s14, 0x4000
	s_addc_u32 s15, s15, 0
	global_load_dwordx4 v[40:43], v2, s[10:11] offset:0
	global_load_dwordx4 v[44:47], v2, s[10:11] offset:1024
	global_load_dwordx4 v[48:51], v2, s[10:11] offset:2048
	global_load_dwordx4 v[52:55], v2, s[10:11] offset:3072
	global_load_dwordx4 v[56:59], v2, s[14:15] offset:0
	global_load_dwordx4 v[60:63], v2, s[14:15] offset:1024
	global_load_dwordx4 v[64:67], v2, s[14:15] offset:2048
	global_load_dwordx4 v[68:71], v2, s[14:15] offset:3072
	global_load_dwordx4 v[72:75], v2, s[16:17] offset:0
	global_load_dwordx4 v[76:79], v2, s[16:17] offset:1024
	global_load_dwordx4 v[80:83], v2, s[16:17] offset:2048
	global_load_dwordx4 v[84:87], v2, s[16:17] offset:3072
	s_waitcnt vmcnt(0)
.Ln2_loop:
	s_add_i32 s4, s7, s37
	s_cmp_lt_i32 s4, s6
	s_cbranch_scc0 .Ln2_last0
	s_cmp_lt_u32 s4, 0x8000
	s_cselect_b32 s10, s22, s24
	s_cselect_b32 s11, s23, s25
	s_cselect_b32 s5, s4, 0x8000
	s_and_b32 s26, s4, 0x7fff
	s_lshl_b32 s27, s26, 12
	s_lshr_b32 s26, s26, 20
	s_add_u32 s10, s10, s27
	s_addc_u32 s11, s11, s26
	s_lshr_b32 s5, s5, 11
	s_add_i32 s5, s5, s54
	s_mul_i32 s5, s5, 0x6000
	s_add_u32 s14, s20, s5
	s_addc_u32 s15, s21, 0
	s_add_u32 s16, s14, 0x3000
	s_addc_u32 s17, s15, 0
	s_add_u32 s14, s14, 0x4000
	s_addc_u32 s15, s15, 0
	global_load_dwordx4 v[88:91], v2, s[10:11] offset:0
	global_load_dwordx4 v[92:95], v2, s[10:11] offset:1024
	global_load_dwordx4 v[96:99], v2, s[10:11] offset:2048
	global_load_dwordx4 v[100:103], v2, s[10:11] offset:3072
	global_load_dwordx4 v[104:107], v2, s[14:15] offset:0
	global_load_dwordx4 v[108:111], v2, s[14:15] offset:1024
	global_load_dwordx4 v[112:115], v2, s[14:15] offset:2048
	global_load_dwordx4 v[116:119], v2, s[14:15] offset:3072
	global_load_dwordx4 v[120:123], v2, s[16:17] offset:0
	global_load_dwordx4 v[124:127], v2, s[16:17] offset:1024
	global_load_dwordx4 v[128:131], v2, s[16:17] offset:2048
	global_load_dwordx4 v[132:135], v2, s[16:17] offset:3072
	v_mul_f32_e32 v12, v40, v40
	v_fmac_f32_e32 v12, v41, v41
	v_fmac_f32_e32 v12, v42, v42
	v_fmac_f32_e32 v12, v43, v43
	v_fmac_f32_e32 v12, v44, v44
	v_fmac_f32_e32 v12, v45, v45
	v_fmac_f32_e32 v12, v46, v46
	v_fmac_f32_e32 v12, v47, v47
	v_fmac_f32_e32 v12, v48, v48
	v_fmac_f32_e32 v12, v49, v49
	v_fmac_f32_e32 v12, v50, v50
	v_fmac_f32_e32 v12, v51, v51
	v_fmac_f32_e32 v12, v52, v52
	v_fmac_f32_e32 v12, v53, v53
	v_fmac_f32_e32 v12, v54, v54
	v_fmac_f32_e32 v12, v55, v55
	ds_bpermute_b32 v13, v4, v12
	s_waitcnt lgkmcnt(0)
	v_add_f32_e32 v12, v12, v13
	ds_bpermute_b32 v13, v5, v12
	s_waitcnt lgkmcnt(0)
	v_add_f32_e32 v12, v12, v13
	ds_bpermute_b32 v13, v6, v12
	s_waitcnt lgkmcnt(0)
	v_add_f32_e32 v12, v12, v13
	ds_bpermute_b32 v13, v7, v12
	s_waitcnt lgkmcnt(0)
	v_add_f32_e32 v12, v12, v13
	ds_bpermute_b32 v13, v8, v12
	s_waitcnt lgkmcnt(0)
	v_add_f32_e32 v12, v12, v13
	ds_bpermute_b32 v13, v9, v12
	s_waitcnt lgkmcnt(0)
	v_add_f32_e32 v12, v12, v13
	v_fmamk_f32 v12, v12, 0x3a800000, v213
	v_cmp_gt_f32_e32 vcc, s38, v12
	v_mul_f32_e32 v13, 0x4b800000, v12
	s_nop 0
	v_cndmask_b32_e32 v12, v12, v13, vcc
	v_rsq_f32_e32 v12, v12
	s_nop 0
	v_mul_f32_e32 v13, 0x45800000, v12
	v_cndmask_b32_e32 v14, v12, v13, vcc
	s_lshl_b32 s12, s7, 11
	s_lshr_b32 s13, s7, 21
	s_add_u32 s12, s64, s12
	s_addc_u32 s13, s65, s13
	v_pk_mul_f32 v[40:41], v[40:41], v[14:15] op_sel_hi:[1,0]
	v_pk_mul_f32 v[40:41], v[20:21], v[40:41]
	v_pk_add_f32 v[56:57], v[56:57], 1.0 op_sel_hi:[1,0]
	v_pk_fma_f32 v[40:41], v[56:57], v[40:41], v[72:73]
	v_pk_mul_f32 v[42:43], v[42:43], v[14:15] op_sel_hi:[1,0]
	v_pk_mul_f32 v[42:43], v[22:23], v[42:43]
	v_pk_add_f32 v[58:59], v[58:59], 1.0 op_sel_hi:[1,0]
	v_pk_fma_f32 v[42:43], v[58:59], v[42:43], v[74:75]
	v_cvt_pk_f16_f32 v40, v40, v41
	v_cvt_pk_f16_f32 v41, v42, v43
	global_store_dwordx2 v3, v[40:41], s[12:13] offset:0
	v_pk_mul_f32 v[44:45], v[44:45], v[14:15] op_sel_hi:[1,0]
	v_pk_mul_f32 v[44:45], v[24:25], v[44:45]
	v_pk_add_f32 v[60:61], v[60:61], 1.0 op_sel_hi:[1,0]
	v_pk_fma_f32 v[44:45], v[60:61], v[44:45], v[76:77]
	v_pk_mul_f32 v[46:47], v[46:47], v[14:15] op_sel_hi:[1,0]
	v_pk_mul_f32 v[46:47], v[26:27], v[46:47]
	v_pk_add_f32 v[62:63], v[62:63], 1.0 op_sel_hi:[1,0]
	v_pk_fma_f32 v[46:47], v[62:63], v[46:47], v[78:79]
	v_cvt_pk_f16_f32 v44, v44, v45
	v_cvt_pk_f16_f32 v45, v46, v47
	global_store_dwordx2 v3, v[44:45], s[12:13] offset:512
	v_pk_mul_f32 v[48:49], v[48:49], v[14:15] op_sel_hi:[1,0]
	v_pk_mul_f32 v[48:49], v[28:29], v[48:49]
	v_pk_add_f32 v[64:65], v[64:65], 1.0 op_sel_hi:[1,0]
	v_pk_fma_f32 v[48:49], v[64:65], v[48:49], v[80:81]
	v_pk_mul_f32 v[50:51], v[50:51], v[14:15] op_sel_hi:[1,0]
	v_pk_mul_f32 v[50:51], v[30:31], v[50:51]
	v_pk_add_f32 v[66:67], v[66:67], 1.0 op_sel_hi:[1,0]
	v_pk_fma_f32 v[50:51], v[66:67], v[50:51], v[82:83]
	v_cvt_pk_f16_f32 v48, v48, v49
	v_cvt_pk_f16_f32 v49, v50, v51
	global_store_dwordx2 v3, v[48:49], s[12:13] offset:1024
	v_pk_mul_f32 v[52:53], v[52:53], v[14:15] op_sel_hi:[1,0]
	v_pk_mul_f32 v[52:53], v[32:33], v[52:53]
	v_pk_add_f32 v[68:69], v[68:69], 1.0 op_sel_hi:[1,0]
	v_pk_fma_f32 v[52:53], v[68:69], v[52:53], v[84:85]
	v_pk_mul_f32 v[54:55], v[54:55], v[14:15] op_sel_hi:[1,0]
	v_pk_mul_f32 v[54:55], v[34:35], v[54:55]
	v_pk_add_f32 v[70:71], v[70:71], 1.0 op_sel_hi:[1,0]
	v_pk_fma_f32 v[54:55], v[70:71], v[54:55], v[86:87]
	v_cvt_pk_f16_f32 v52, v52, v53
	v_cvt_pk_f16_f32 v53, v54, v55
	global_store_dwordx2 v3, v[52:53], s[12:13] offset:1536
	s_waitcnt vmcnt(4)
	s_mov_b32 s7, s4
	s_add_i32 s4, s7, s37
	s_cmp_lt_i32 s4, s6
	s_cbranch_scc0 .Ln2_last1
	s_cmp_lt_u32 s4, 0x8000
	s_cselect_b32 s10, s22, s24
	s_cselect_b32 s11, s23, s25
	s_cselect_b32 s5, s4, 0x8000
	s_and_b32 s26, s4, 0x7fff
	s_lshl_b32 s27, s26, 12
	s_lshr_b32 s26, s26, 20
	s_add_u32 s10, s10, s27
	s_addc_u32 s11, s11, s26
	s_lshr_b32 s5, s5, 11
	s_add_i32 s5, s5, s54
	s_mul_i32 s5, s5, 0x6000
	s_add_u32 s14, s20, s5
	s_addc_u32 s15, s21, 0
	s_add_u32 s16, s14, 0x3000
	s_addc_u32 s17, s15, 0
	s_add_u32 s14, s14, 0x4000
	s_addc_u32 s15, s15, 0
	global_load_dwordx4 v[40:43], v2, s[10:11] offset:0
	global_load_dwordx4 v[44:47], v2, s[10:11] offset:1024
	global_load_dwordx4 v[48:51], v2, s[10:11] offset:2048
	global_load_dwordx4 v[52:55], v2, s[10:11] offset:3072
	global_load_dwordx4 v[56:59], v2, s[14:15] offset:0
	global_load_dwordx4 v[60:63], v2, s[14:15] offset:1024
	global_load_dwordx4 v[64:67], v2, s[14:15] offset:2048
	global_load_dwordx4 v[68:71], v2, s[14:15] offset:3072
	global_load_dwordx4 v[72:75], v2, s[16:17] offset:0
	global_load_dwordx4 v[76:79], v2, s[16:17] offset:1024
	global_load_dwordx4 v[80:83], v2, s[16:17] offset:2048
	global_load_dwordx4 v[84:87], v2, s[16:17] offset:3072
	v_mul_f32_e32 v12, v88, v88
	v_fmac_f32_e32 v12, v89, v89
	v_fmac_f32_e32 v12, v90, v90
	v_fmac_f32_e32 v12, v91, v91
	v_fmac_f32_e32 v12, v92, v92
	v_fmac_f32_e32 v12, v93, v93
	v_fmac_f32_e32 v12, v94, v94
	v_fmac_f32_e32 v12, v95, v95
	v_fmac_f32_e32 v12, v96, v96
	v_fmac_f32_e32 v12, v97, v97
	v_fmac_f32_e32 v12, v98, v98
	v_fmac_f32_e32 v12, v99, v99
	v_fmac_f32_e32 v12, v100, v100
	v_fmac_f32_e32 v12, v101, v101
	v_fmac_f32_e32 v12, v102, v102
	v_fmac_f32_e32 v12, v103, v103
	ds_bpermute_b32 v13, v4, v12
	s_waitcnt lgkmcnt(0)
	v_add_f32_e32 v12, v12, v13
	ds_bpermute_b32 v13, v5, v12
	s_waitcnt lgkmcnt(0)
	v_add_f32_e32 v12, v12, v13
	ds_bpermute_b32 v13, v6, v12
	s_waitcnt lgkmcnt(0)
	v_add_f32_e32 v12, v12, v13
	ds_bpermute_b32 v13, v7, v12
	s_waitcnt lgkmcnt(0)
	v_add_f32_e32 v12, v12, v13
	ds_bpermute_b32 v13, v8, v12
	s_waitcnt lgkmcnt(0)
	v_add_f32_e32 v12, v12, v13
	ds_bpermute_b32 v13, v9, v12
	s_waitcnt lgkmcnt(0)
	v_add_f32_e32 v12, v12, v13
	v_fmamk_f32 v12, v12, 0x3a800000, v213
	v_cmp_gt_f32_e32 vcc, s38, v12
	v_mul_f32_e32 v13, 0x4b800000, v12
	s_nop 0
	v_cndmask_b32_e32 v12, v12, v13, vcc
	v_rsq_f32_e32 v12, v12
	s_nop 0
	v_mul_f32_e32 v13, 0x45800000, v12
	v_cndmask_b32_e32 v14, v12, v13, vcc
	s_lshl_b32 s12, s7, 11
	s_lshr_b32 s13, s7, 21
	s_add_u32 s12, s64, s12
	s_addc_u32 s13, s65, s13
	v_pk_mul_f32 v[88:89], v[88:89], v[14:15] op_sel_hi:[1,0]
	v_pk_mul_f32 v[88:89], v[20:21], v[88:89]
	v_pk_add_f32 v[104:105], v[104:105], 1.0 op_sel_hi:[1,0]
	v_pk_fma_f32 v[88:89], v[104:105], v[88:89], v[120:121]
	v_pk_mul_f32 v[90:91], v[90:91], v[14:15] op_sel_hi:[1,0]
	v_pk_mul_f32 v[90:91], v[22:23], v[90:91]
	v_pk_add_f32 v[106:107], v[106:107], 1.0 op_sel_hi:[1,0]
	v_pk_fma_f32 v[90:91], v[106:107], v[90:91], v[122:123]
	v_cvt_pk_f16_f32 v88, v88, v89
	v_cvt_pk_f16_f32 v89, v90, v91
	global_store_dwordx2 v3, v[88:89], s[12:13] offset:0
	v_pk_mul_f32 v[92:93], v[92:93], v[14:15] op_sel_hi:[1,0]
	v_pk_mul_f32 v[92:93], v[24:25], v[92:93]
	v_pk_add_f32 v[108:109], v[108:109], 1.0 op_sel_hi:[1,0]
	v_pk_fma_f32 v[92:93], v[108:109], v[92:93], v[124:125]
	v_pk_mul_f32 v[94:95], v[94:95], v[14:15] op_sel_hi:[1,0]
	v_pk_mul_f32 v[94:95], v[26:27], v[94:95]
	v_pk_add_f32 v[110:111], v[110:111], 1.0 op_sel_hi:[1,0]
	v_pk_fma_f32 v[94:95], v[110:111], v[94:95], v[126:127]
	v_cvt_pk_f16_f32 v92, v92, v93
	v_cvt_pk_f16_f32 v93, v94, v95
	global_store_dwordx2 v3, v[92:93], s[12:13] offset:512
	v_pk_mul_f32 v[96:97], v[96:97], v[14:15] op_sel_hi:[1,0]
	v_pk_mul_f32 v[96:97], v[28:29], v[96:97]
	v_pk_add_f32 v[112:113], v[112:113], 1.0 op_sel_hi:[1,0]
	v_pk_fma_f32 v[96:97], v[112:113], v[96:97], v[128:129]
	v_pk_mul_f32 v[98:99], v[98:99], v[14:15] op_sel_hi:[1,0]
	v_pk_mul_f32 v[98:99], v[30:31], v[98:99]
	v_pk_add_f32 v[114:115], v[114:115], 1.0 op_sel_hi:[1,0]
	v_pk_fma_f32 v[98:99], v[114:115], v[98:99], v[130:131]
	v_cvt_pk_f16_f32 v96, v96, v97
	v_cvt_pk_f16_f32 v97, v98, v99
	global_store_dwordx2 v3, v[96:97], s[12:13] offset:1024
	v_pk_mul_f32 v[100:101], v[100:101], v[14:15] op_sel_hi:[1,0]
	v_pk_mul_f32 v[100:101], v[32:33], v[100:101]
	v_pk_add_f32 v[116:117], v[116:117], 1.0 op_sel_hi:[1,0]
	v_pk_fma_f32 v[100:101], v[116:117], v[100:101], v[132:133]
	v_pk_mul_f32 v[102:103], v[102:103], v[14:15] op_sel_hi:[1,0]
	v_pk_mul_f32 v[102:103], v[34:35], v[102:103]
	v_pk_add_f32 v[118:119], v[118:119], 1.0 op_sel_hi:[1,0]
	v_pk_fma_f32 v[102:103], v[118:119], v[102:103], v[134:135]
	v_cvt_pk_f16_f32 v100, v100, v101
	v_cvt_pk_f16_f32 v101, v102, v103
	global_store_dwordx2 v3, v[100:101], s[12:13] offset:1536
	s_waitcnt vmcnt(4)
	s_mov_b32 s7, s4
	s_branch .Ln2_loop
.Ln2_last0:
	v_mul_f32_e32 v12, v40, v40
	v_fmac_f32_e32 v12, v41, v41
	v_fmac_f32_e32 v12, v42, v42
	v_fmac_f32_e32 v12, v43, v43
	v_fmac_f32_e32 v12, v44, v44
	v_fmac_f32_e32 v12, v45, v45
	v_fmac_f32_e32 v12, v46, v46
	v_fmac_f32_e32 v12, v47, v47
	v_fmac_f32_e32 v12, v48, v48
	v_fmac_f32_e32 v12, v49, v49
	v_fmac_f32_e32 v12, v50, v50
	v_fmac_f32_e32 v12, v51, v51
	v_fmac_f32_e32 v12, v52, v52
	v_fmac_f32_e32 v12, v53, v53
	v_fmac_f32_e32 v12, v54, v54
	v_fmac_f32_e32 v12, v55, v55
	ds_bpermute_b32 v13, v4, v12
	s_waitcnt lgkmcnt(0)
	v_add_f32_e32 v12, v12, v13
	ds_bpermute_b32 v13, v5, v12
	s_waitcnt lgkmcnt(0)
	v_add_f32_e32 v12, v12, v13
	ds_bpermute_b32 v13, v6, v12
	s_waitcnt lgkmcnt(0)
	v_add_f32_e32 v12, v12, v13
	ds_bpermute_b32 v13, v7, v12
	s_waitcnt lgkmcnt(0)
	v_add_f32_e32 v12, v12, v13
	ds_bpermute_b32 v13, v8, v12
	s_waitcnt lgkmcnt(0)
	v_add_f32_e32 v12, v12, v13
	ds_bpermute_b32 v13, v9, v12
	s_waitcnt lgkmcnt(0)
	v_add_f32_e32 v12, v12, v13
	v_fmamk_f32 v12, v12, 0x3a800000, v213
	v_cmp_gt_f32_e32 vcc, s38, v12
	v_mul_f32_e32 v13, 0x4b800000, v12
	s_nop 0
	v_cndmask_b32_e32 v12, v12, v13, vcc
	v_rsq_f32_e32 v12, v12
	s_nop 0
	v_mul_f32_e32 v13, 0x45800000, v12
	v_cndmask_b32_e32 v14, v12, v13, vcc
	s_lshl_b32 s12, s7, 11
	s_lshr_b32 s13, s7, 21
	s_add_u32 s12, s64, s12
	s_addc_u32 s13, s65, s13
	v_pk_mul_f32 v[40:41], v[40:41], v[14:15] op_sel_hi:[1,0]
	v_pk_mul_f32 v[40:41], v[20:21], v[40:41]
	v_pk_add_f32 v[56:57], v[56:57], 1.0 op_sel_hi:[1,0]
	v_pk_fma_f32 v[40:41], v[56:57], v[40:41], v[72:73]
	v_pk_mul_f32 v[42:43], v[42:43], v[14:15] op_sel_hi:[1,0]
	v_pk_mul_f32 v[42:43], v[22:23], v[42:43]
	v_pk_add_f32 v[58:59], v[58:59], 1.0 op_sel_hi:[1,0]
	v_pk_fma_f32 v[42:43], v[58:59], v[42:43], v[74:75]
	v_cvt_pk_f16_f32 v40, v40, v41
	v_cvt_pk_f16_f32 v41, v42, v43
	global_store_dwordx2 v3, v[40:41], s[12:13] offset:0
	v_pk_mul_f32 v[44:45], v[44:45], v[14:15] op_sel_hi:[1,0]
	v_pk_mul_f32 v[44:45], v[24:25], v[44:45]
	v_pk_add_f32 v[60:61], v[60:61], 1.0 op_sel_hi:[1,0]
	v_pk_fma_f32 v[44:45], v[60:61], v[44:45], v[76:77]
	v_pk_mul_f32 v[46:47], v[46:47], v[14:15] op_sel_hi:[1,0]
	v_pk_mul_f32 v[46:47], v[26:27], v[46:47]
	v_pk_add_f32 v[62:63], v[62:63], 1.0 op_sel_hi:[1,0]
	v_pk_fma_f32 v[46:47], v[62:63], v[46:47], v[78:79]
	v_cvt_pk_f16_f32 v44, v44, v45
	v_cvt_pk_f16_f32 v45, v46, v47
	global_store_dwordx2 v3, v[44:45], s[12:13] offset:512
	v_pk_mul_f32 v[48:49], v[48:49], v[14:15] op_sel_hi:[1,0]
	v_pk_mul_f32 v[48:49], v[28:29], v[48:49]
	v_pk_add_f32 v[64:65], v[64:65], 1.0 op_sel_hi:[1,0]
	v_pk_fma_f32 v[48:49], v[64:65], v[48:49], v[80:81]
	v_pk_mul_f32 v[50:51], v[50:51], v[14:15] op_sel_hi:[1,0]
	v_pk_mul_f32 v[50:51], v[30:31], v[50:51]
	v_pk_add_f32 v[66:67], v[66:67], 1.0 op_sel_hi:[1,0]
	v_pk_fma_f32 v[50:51], v[66:67], v[50:51], v[82:83]
	v_cvt_pk_f16_f32 v48, v48, v49
	v_cvt_pk_f16_f32 v49, v50, v51
	global_store_dwordx2 v3, v[48:49], s[12:13] offset:1024
	v_pk_mul_f32 v[52:53], v[52:53], v[14:15] op_sel_hi:[1,0]
	v_pk_mul_f32 v[52:53], v[32:33], v[52:53]
	v_pk_add_f32 v[68:69], v[68:69], 1.0 op_sel_hi:[1,0]
	v_pk_fma_f32 v[52:53], v[68:69], v[52:53], v[84:85]
	v_pk_mul_f32 v[54:55], v[54:55], v[14:15] op_sel_hi:[1,0]
	v_pk_mul_f32 v[54:55], v[34:35], v[54:55]
	v_pk_add_f32 v[70:71], v[70:71], 1.0 op_sel_hi:[1,0]
	v_pk_fma_f32 v[54:55], v[70:71], v[54:55], v[86:87]
	v_cvt_pk_f16_f32 v52, v52, v53
	v_cvt_pk_f16_f32 v53, v54, v55
	global_store_dwordx2 v3, v[52:53], s[12:13] offset:1536
	s_branch .Ln2_done
.Ln2_last1:
	v_mul_f32_e32 v12, v88, v88
	v_fmac_f32_e32 v12, v89, v89
	v_fmac_f32_e32 v12, v90, v90
	v_fmac_f32_e32 v12, v91, v91
	v_fmac_f32_e32 v12, v92, v92
	v_fmac_f32_e32 v12, v93, v93
	v_fmac_f32_e32 v12, v94, v94
	v_fmac_f32_e32 v12, v95, v95
	v_fmac_f32_e32 v12, v96, v96
	v_fmac_f32_e32 v12, v97, v97
	v_fmac_f32_e32 v12, v98, v98
	v_fmac_f32_e32 v12, v99, v99
	v_fmac_f32_e32 v12, v100, v100
	v_fmac_f32_e32 v12, v101, v101
	v_fmac_f32_e32 v12, v102, v102
	v_fmac_f32_e32 v12, v103, v103
	ds_bpermute_b32 v13, v4, v12
	s_waitcnt lgkmcnt(0)
	v_add_f32_e32 v12, v12, v13
	ds_bpermute_b32 v13, v5, v12
	s_waitcnt lgkmcnt(0)
	v_add_f32_e32 v12, v12, v13
	ds_bpermute_b32 v13, v6, v12
	s_waitcnt lgkmcnt(0)
	v_add_f32_e32 v12, v12, v13
	ds_bpermute_b32 v13, v7, v12
	s_waitcnt lgkmcnt(0)
	v_add_f32_e32 v12, v12, v13
	ds_bpermute_b32 v13, v8, v12
	s_waitcnt lgkmcnt(0)
	v_add_f32_e32 v12, v12, v13
	ds_bpermute_b32 v13, v9, v12
	s_waitcnt lgkmcnt(0)
	v_add_f32_e32 v12, v12, v13
	v_fmamk_f32 v12, v12, 0x3a800000, v213
	v_cmp_gt_f32_e32 vcc, s38, v12
	v_mul_f32_e32 v13, 0x4b800000, v12
	s_nop 0
	v_cndmask_b32_e32 v12, v12, v13, vcc
	v_rsq_f32_e32 v12, v12
	s_nop 0
	v_mul_f32_e32 v13, 0x45800000, v12
	v_cndmask_b32_e32 v14, v12, v13, vcc
	s_lshl_b32 s12, s7, 11
	s_lshr_b32 s13, s7, 21
	s_add_u32 s12, s64, s12
	s_addc_u32 s13, s65, s13
	v_pk_mul_f32 v[88:89], v[88:89], v[14:15] op_sel_hi:[1,0]
	v_pk_mul_f32 v[88:89], v[20:21], v[88:89]
	v_pk_add_f32 v[104:105], v[104:105], 1.0 op_sel_hi:[1,0]
	v_pk_fma_f32 v[88:89], v[104:105], v[88:89], v[120:121]
	v_pk_mul_f32 v[90:91], v[90:91], v[14:15] op_sel_hi:[1,0]
	v_pk_mul_f32 v[90:91], v[22:23], v[90:91]
	v_pk_add_f32 v[106:107], v[106:107], 1.0 op_sel_hi:[1,0]
	v_pk_fma_f32 v[90:91], v[106:107], v[90:91], v[122:123]
	v_cvt_pk_f16_f32 v88, v88, v89
	v_cvt_pk_f16_f32 v89, v90, v91
	global_store_dwordx2 v3, v[88:89], s[12:13] offset:0
	v_pk_mul_f32 v[92:93], v[92:93], v[14:15] op_sel_hi:[1,0]
	v_pk_mul_f32 v[92:93], v[24:25], v[92:93]
	v_pk_add_f32 v[108:109], v[108:109], 1.0 op_sel_hi:[1,0]
	v_pk_fma_f32 v[92:93], v[108:109], v[92:93], v[124:125]
	v_pk_mul_f32 v[94:95], v[94:95], v[14:15] op_sel_hi:[1,0]
	v_pk_mul_f32 v[94:95], v[26:27], v[94:95]
	v_pk_add_f32 v[110:111], v[110:111], 1.0 op_sel_hi:[1,0]
	v_pk_fma_f32 v[94:95], v[110:111], v[94:95], v[126:127]
	v_cvt_pk_f16_f32 v92, v92, v93
	v_cvt_pk_f16_f32 v93, v94, v95
	global_store_dwordx2 v3, v[92:93], s[12:13] offset:512
	v_pk_mul_f32 v[96:97], v[96:97], v[14:15] op_sel_hi:[1,0]
	v_pk_mul_f32 v[96:97], v[28:29], v[96:97]
	v_pk_add_f32 v[112:113], v[112:113], 1.0 op_sel_hi:[1,0]
	v_pk_fma_f32 v[96:97], v[112:113], v[96:97], v[128:129]
	v_pk_mul_f32 v[98:99], v[98:99], v[14:15] op_sel_hi:[1,0]
	v_pk_mul_f32 v[98:99], v[30:31], v[98:99]
	v_pk_add_f32 v[114:115], v[114:115], 1.0 op_sel_hi:[1,0]
	v_pk_fma_f32 v[98:99], v[114:115], v[98:99], v[130:131]
	v_cvt_pk_f16_f32 v96, v96, v97
	v_cvt_pk_f16_f32 v97, v98, v99
	global_store_dwordx2 v3, v[96:97], s[12:13] offset:1024
	v_pk_mul_f32 v[100:101], v[100:101], v[14:15] op_sel_hi:[1,0]
	v_pk_mul_f32 v[100:101], v[32:33], v[100:101]
	v_pk_add_f32 v[116:117], v[116:117], 1.0 op_sel_hi:[1,0]
	v_pk_fma_f32 v[100:101], v[116:117], v[100:101], v[132:133]
	v_pk_mul_f32 v[102:103], v[102:103], v[14:15] op_sel_hi:[1,0]
	v_pk_mul_f32 v[102:103], v[34:35], v[102:103]
	v_pk_add_f32 v[118:119], v[118:119], 1.0 op_sel_hi:[1,0]
	v_pk_fma_f32 v[102:103], v[118:119], v[102:103], v[134:135]
	v_cvt_pk_f16_f32 v100, v100, v101
	v_cvt_pk_f16_f32 v101, v102, v103
	global_store_dwordx2 v3, v[100:101], s[12:13] offset:1536
.Ln2_done:
	v_readlane_b32 s12, v254, 0
	v_readlane_b32 s13, v254, 1
	v_readlane_b32 s14, v254, 2
	v_readlane_b32 s15, v254, 3
	v_readlane_b32 s16, v254, 4
	v_readlane_b32 s17, v254, 5
	v_readlane_b32 s18, v254, 6
	v_readlane_b32 s19, v254, 7
	v_readlane_b32 s20, v254, 8
	v_readlane_b32 s21, v254, 9
	v_readlane_b32 s22, v254, 10
	v_readlane_b32 s23, v254, 11
	v_readlane_b32 s24, v254, 12
	v_readlane_b32 s25, v254, 13
	v_readlane_b32 s26, v254, 14
	v_readlane_b32 s27, v254, 15
	s_branch .LBB0_1078
